# scan split loop: the two xor-32 ds_bpermute butterflies replaced by v_permlane32_swap pairs (no LDS round trip)
# speedup vs baseline: 1.0139x; 1.0139x over previous
; __device__ __forceinline__ unsigned cvt_pk(float lo, float hi) { unsigned r; asm volatile("v_cvt_pk_bf16_f32 %0, %1, %2" : "=v"(r) : "v"(lo), "v"(hi)); return r; }
; template <int SPLIT> __device__ __forceinline__ void scan_item(const Params& p, unsigned char* smem, const int item, const int vh) {
;     ...
;             __syncthreads();
;             const float m_old = sc[0], M127 = sc[1];
;             const float decay = __expf(m_old - M127);
;             {
;                 const f32x4 a4 = *(const f32x4*)(a_s + sp * 4);
;                 float wsv[4];
; #pragma unroll
;                 for (int i = 0; i < 4; ++i) wsv[i] = __expf(a4[i] - M127);
; #pragma unroll
;                 for (int i = 0; i < 4; ++i) { const u32x4 k = kreg[i]; u32x4 w;
;                     w.x = cvt_pk(bflo(k.x) * wsv[i], bfhi(k.x) * wsv[i]); w.y = cvt_pk(bflo(k.y) * wsv[i], bfhi(k.y) * wsv[i]);
;                     w.z = cvt_pk(bflo(k.z) * wsv[i], bfhi(k.z) * wsv[i]); w.w = cvt_pk(bflo(k.w) * wsv[i], bfhi(k.w) * wsv[i]);
;                     *(u32x4*)(KP + swz(sp * 4 + i, ch)) = w; }
; #pragma unroll
;                 for (int e2 = 0; e2 < 4; ++e2) {
;                     const unsigned k0 = kreg[0][e2], k1 = kreg[1][e2], k2 = kreg[2][e2], k3 = kreg[3][e2];
;                     const unsigned v0 = vreg[0][e2], v1 = vreg[1][e2], v2 = vreg[2][e2], v3 = vreg[3][e2];
;                     const int d0 = ch * 8 + 2 * e2, d1 = d0 + 1; const int co = (sp & 1) * 8;
;                     u32x2 o;
;                     o.x = cvt_pk(bflo(k0) * wsv[0], bflo(k1) * wsv[1]); o.y = cvt_pk(bflo(k2) * wsv[2], bflo(k3) * wsv[3]);
;                     *(u32x2*)(KT + swz(d0, sp >> 1) + co) = o;
;                     o.x = cvt_pk(bfhi(k0) * wsv[0], bfhi(k1) * wsv[1]); o.y = cvt_pk(bfhi(k2) * wsv[2], bfhi(k3) * wsv[3]);
;                     *(u32x2*)(KT + swz(d1, sp >> 1) + co) = o;
;                     o.x = (v0 & 0xffffu) | (v1 << 16); o.y = (v2 & 0xffffu) | (v3 << 16);
;                     *(u32x2*)(VT + swz(d0, sp >> 1) + co) = o;
;                     o.x = (v0 >> 16) | (v1 & 0xffff0000u); o.y = (v2 >> 16) | (v3 & 0xffff0000u);
;                     *(u32x2*)(VT + swz(d1, sp >> 1) + co) = o;
;                 }
;             }
;             const size_t rowl = (size_t)(rfirst + rstep * (j * 128 + wid * 16 + li));
.LBB0_316:
	s_or_b64 exec, exec, s[86:87]
	v_mov_b32_e32 v67, s92
	s_waitcnt lgkmcnt(0)
	s_barrier
	ds_read_b64 v[86:87], v67
	ds_read_b128 v[88:91], v98
	s_waitcnt vmcnt(11)
	v_lshlrev_b32_e32 v92, 16, v45
	v_and_b32_e32 v45, 0xffff0000, v45
	v_lshlrev_b32_e32 v94, 16, v46
	v_and_b32_e32 v46, 0xffff0000, v46
	s_waitcnt lgkmcnt(0)
	v_sub_f32_e32 v67, v88, v87
	v_mul_f32_e32 v67, 0x3fb8aa3b, v67
	v_exp_f32_e32 v67, v67
	v_sub_f32_e32 v84, v89, v87
	v_mul_f32_e32 v84, 0x3fb8aa3b, v84
	v_exp_f32_e32 v84, v84
	v_sub_f32_e32 v88, v90, v87
	v_mul_f32_e32 v88, 0x3fb8aa3b, v88
	v_lshlrev_b32_e32 v90, 16, v44
	v_and_b32_e32 v44, 0xffff0000, v44
	v_exp_f32_e32 v88, v88
	v_sub_f32_e32 v89, v91, v87
	v_mul_f32_e32 v90, v67, v90
	v_mul_f32_e32 v91, v67, v44
	v_cvt_pk_bf16_f32 v44, v90, v91
	v_mul_f32_e32 v92, v67, v92
	v_mul_f32_e32 v93, v67, v45
	v_cvt_pk_bf16_f32 v45, v92, v93
	v_mul_f32_e32 v94, v67, v94
	v_mul_f32_e32 v95, v67, v46
	v_cvt_pk_bf16_f32 v46, v94, v95
	v_lshlrev_b32_e32 v151, 16, v47
	v_and_b32_e32 v47, 0xffff0000, v47
	v_mul_f32_e32 v89, 0x3fb8aa3b, v89
	v_mul_f32_e32 v151, v67, v151
	v_mul_f32_e32 v67, v67, v47
	v_cvt_pk_bf16_f32 v47, v151, v67
	ds_write_b128 v133, v[44:47]
	s_waitcnt vmcnt(10)
	v_lshlrev_b32_e32 v44, 16, v40
	v_and_b32_e32 v40, 0xffff0000, v40
	v_lshlrev_b32_e32 v46, 16, v41
	v_and_b32_e32 v41, 0xffff0000, v41
	v_lshlrev_b32_e32 v152, 16, v42
	v_and_b32_e32 v42, 0xffff0000, v42
	v_exp_f32_e32 v89, v89
	v_mul_f32_e32 v44, v84, v44
	v_mul_f32_e32 v45, v84, v40
	v_cvt_pk_bf16_f32 v40, v44, v45
	v_mul_f32_e32 v46, v84, v46
	v_mul_f32_e32 v47, v84, v41
	v_cvt_pk_bf16_f32 v41, v46, v47
	v_mul_f32_e32 v152, v84, v152
	v_mul_f32_e32 v153, v84, v42
	v_cvt_pk_bf16_f32 v42, v152, v153
	v_lshlrev_b32_e32 v154, 16, v43
	v_and_b32_e32 v43, 0xffff0000, v43
	v_mul_f32_e32 v154, v84, v154
	v_mul_f32_e32 v84, v84, v43
	v_cvt_pk_bf16_f32 v43, v154, v84
	ds_write_b128 v134, v[40:43]
	s_waitcnt vmcnt(9)
	v_lshlrev_b32_e32 v40, 16, v36
	v_and_b32_e32 v36, 0xffff0000, v36
	v_lshlrev_b32_e32 v42, 16, v37
	v_and_b32_e32 v37, 0xffff0000, v37
	v_lshlrev_b32_e32 v155, 16, v38
	v_and_b32_e32 v38, 0xffff0000, v38
	v_mul_f32_e32 v40, v88, v40
	v_mul_f32_e32 v41, v88, v36
	v_cvt_pk_bf16_f32 v36, v40, v41
	v_mul_f32_e32 v42, v88, v42
	v_mul_f32_e32 v43, v88, v37
	v_cvt_pk_bf16_f32 v37, v42, v43
	v_mul_f32_e32 v155, v88, v155
	v_mul_f32_e32 v156, v88, v38
	v_cvt_pk_bf16_f32 v38, v155, v156
	v_lshlrev_b32_e32 v157, 16, v39
	v_and_b32_e32 v39, 0xffff0000, v39
	v_mul_f32_e32 v157, v88, v157
	v_mul_f32_e32 v88, v88, v39
	v_cvt_pk_bf16_f32 v39, v157, v88
	ds_write_b128 v135, v[36:39]
	s_waitcnt vmcnt(7)
	v_lshlrev_b32_e32 v36, 16, v32
	v_and_b32_e32 v32, 0xffff0000, v32
	v_lshlrev_b32_e32 v38, 16, v33
	v_and_b32_e32 v33, 0xffff0000, v33
	v_lshlrev_b32_e32 v158, 16, v34
	v_and_b32_e32 v34, 0xffff0000, v34
	v_mul_f32_e32 v36, v89, v36
	v_mul_f32_e32 v37, v89, v32
	v_cvt_pk_bf16_f32 v32, v36, v37
	v_mul_f32_e32 v38, v89, v38
	v_mul_f32_e32 v39, v89, v33
	v_cvt_pk_bf16_f32 v33, v38, v39
	v_mul_f32_e32 v158, v89, v158
	v_mul_f32_e32 v159, v89, v34
	v_cvt_pk_bf16_f32 v34, v158, v159
	v_lshlrev_b32_e32 v160, 16, v35
	v_and_b32_e32 v35, 0xffff0000, v35
	v_mul_f32_e32 v160, v89, v160
	v_mul_f32_e32 v89, v89, v35
	v_cvt_pk_bf16_f32 v35, v160, v89
	ds_write_b128 v136, v[32:35]
	v_cvt_pk_bf16_f32 v32, v90, v44
	v_cvt_pk_bf16_f32 v33, v40, v36
	v_add_u32_e32 v34, v102, v123
	ds_write_b64 v34, v[32:33]
	v_cvt_pk_bf16_f32 v32, v91, v45
	v_cvt_pk_bf16_f32 v33, v41, v37
	v_add_u32_e32 v34, v102, v124
	ds_write_b64 v34, v[32:33]
	s_waitcnt vmcnt(4)
	v_lshlrev_b32_e32 v32, 16, v4
	v_lshlrev_b32_e32 v33, 16, v16
	v_and_or_b32 v32, v0, s95, v32
	v_and_or_b32 v33, v8, s95, v33
	v_add_u32_e32 v34, v103, v123
	v_lshrrev_b32_e32 v0, 16, v0
	ds_write_b64 v34, v[32:33] offset:32768
	v_and_or_b32 v32, v4, s94, v0
	v_lshrrev_b32_e32 v0, 16, v8
	v_and_or_b32 v33, v16, s94, v0
	v_add_u32_e32 v0, v103, v124
	ds_write_b64 v0, v[32:33] offset:32768
	v_add_u32_e32 v0, v102, v125
	v_cvt_pk_bf16_f32 v32, v92, v46
	v_cvt_pk_bf16_f32 v33, v42, v38
	ds_write_b64 v0, v[32:33]
	v_add_u32_e32 v0, v102, v126
	v_cvt_pk_bf16_f32 v32, v93, v47
	v_cvt_pk_bf16_f32 v33, v43, v39
	ds_write_b64 v0, v[32:33]
	v_lshlrev_b32_e32 v0, 16, v5
	v_and_or_b32 v32, v1, s95, v0
	v_lshlrev_b32_e32 v0, 16, v17
	v_and_or_b32 v33, v9, s95, v0
	v_add_u32_e32 v0, v103, v125
	ds_write_b64 v0, v[32:33] offset:32768
	v_lshrrev_b32_e32 v0, 16, v1
	v_lshrrev_b32_e32 v1, 16, v9
	v_and_or_b32 v0, v5, s94, v0
	v_and_or_b32 v1, v17, s94, v1
	v_add_u32_e32 v4, v103, v126
	ds_write_b64 v4, v[0:1] offset:32768
	v_cvt_pk_bf16_f32 v0, v94, v152
	v_cvt_pk_bf16_f32 v1, v155, v158
	v_add_u32_e32 v4, v102, v127
	ds_write_b64 v4, v[0:1]
	v_cvt_pk_bf16_f32 v0, v95, v153
	v_cvt_pk_bf16_f32 v1, v156, v159
	v_add_u32_e32 v4, v102, v128
	ds_write_b64 v4, v[0:1]
	v_lshlrev_b32_e32 v0, 16, v6
	v_lshlrev_b32_e32 v1, 16, v18
	v_and_or_b32 v0, v2, s95, v0
	v_and_or_b32 v1, v10, s95, v1
	v_add_u32_e32 v4, v103, v127
	ds_write_b64 v4, v[0:1] offset:32768
	v_lshrrev_b32_e32 v0, 16, v2
	v_lshrrev_b32_e32 v1, 16, v10
	v_and_or_b32 v0, v6, s94, v0
	v_and_or_b32 v1, v18, s94, v1
	v_add_u32_e32 v2, v103, v128
	ds_write_b64 v2, v[0:1] offset:32768
	v_cvt_pk_bf16_f32 v0, v151, v154
	v_cvt_pk_bf16_f32 v1, v157, v160
	v_add_u32_e32 v2, v102, v129
	ds_write_b64 v2, v[0:1]
	v_cvt_pk_bf16_f32 v0, v67, v84
	v_cvt_pk_bf16_f32 v1, v88, v89
	v_add_u32_e32 v2, v102, v130
	ds_write_b64 v2, v[0:1]
	v_lshlrev_b32_e32 v0, 16, v7
	v_lshlrev_b32_e32 v1, 16, v19
	v_and_or_b32 v0, v3, s95, v0
	v_and_or_b32 v1, v11, s95, v1
	v_add_u32_e32 v2, v103, v129
	ds_write_b64 v2, v[0:1] offset:32768
	v_lshrrev_b32_e32 v0, 16, v3
	v_lshrrev_b32_e32 v1, 16, v11
	v_and_or_b32 v0, v7, s94, v0
	v_and_or_b32 v1, v19, s94, v1
	v_add_u32_e32 v2, v103, v130
	s_lshl_b32 s0, vcc_lo, 7
	ds_write_b64 v2, v[0:1] offset:32768
	v_or_b32_e32 v0, s0, v85
	v_mul_lo_u32 v0, v0, s3
	v_add_u32_e32 v4, s33, v0
	v_ashrrev_i32_e32 v5, 31, v4
	v_lshlrev_b64 v[0:1], 10, v[4:5]
	v_add_u32_e32 v8, s3, v4
	v_lshl_add_u64 v[0:1], v[64:65], 0, v[0:1]
	v_ashrrev_i32_e32 v9, 31, v8
	s_waitcnt lgkmcnt(0)
	s_barrier
; #define SCAN_LOAD(j) do { \
;         _Pragma("unroll") for (int i = 0; i < 4; ++i) { const size_t r = (size_t)(rfirst + rstep * ((j) * 128 + sp * 4 + i)); \
;             kreg[i] = *(const u32x4*)(K0 + r * 512 + h * 128 + ch * 8); vreg[i] = *(const u32x4*)(P0 + r * LDP + 1536 + h * 128 + ch * 8); } \
;         } while (0)
; template <int SPLIT> __device__ __forceinline__ void scan_item(const Params& p, unsigned char* smem, const int item, const int vh) {
;     ...
;             SCAN_LOAD(jn);
;             __builtin_amdgcn_sched_barrier(0);
;             const int l = wid * 16 + li;
;             const float Ml = M_s[l], gl = g_s[l];
;             f32x4 acc[8];
; #pragma unroll
;             for (int nb = 0; nb < 8; ++nb) acc[nb] = (f32x4){0.f, 0.f, 0.f, 0.f};
;             mm16<8>(acc, KP, qf, lane);
	global_load_dwordx4 v[44:47], v[0:1], off
	v_mad_i64_i32 v[0:1], s[4:5], v4, s88, v[80:81]
	v_lshlrev_b64 v[4:5], 10, v[8:9]
	v_add_u32_e32 v16, s3, v8
	v_lshl_add_u64 v[4:5], v[64:65], 0, v[4:5]
	v_ashrrev_i32_e32 v17, 31, v16
	global_load_dwordx4 v[40:43], v[4:5], off
	v_mad_i64_i32 v[4:5], s[4:5], v8, s88, v[80:81]
	v_lshlrev_b64 v[8:9], 10, v[16:17]
	v_lshl_add_u64 v[8:9], v[64:65], 0, v[8:9]
	global_load_dwordx4 v[36:39], v[8:9], off
	v_mad_i64_i32 v[8:9], s[4:5], v16, s88, v[80:81]
	v_add_u32_e32 v16, s3, v16
	v_ashrrev_i32_e32 v17, 31, v16
	v_lshlrev_b64 v[18:19], 10, v[16:17]
	v_lshl_add_u64 v[18:19], v[64:65], 0, v[18:19]
	v_mad_i64_i32 v[16:17], s[4:5], v16, s88, v[80:81]
	global_load_dwordx4 v[0:3], v[0:1], off offset:3072
	v_sub_f32_e32 v67, v86, v87
	global_load_dwordx4 v[4:7], v[4:5], off offset:3072
	v_mul_f32_e32 v67, 0x3fb8aa3b, v67
	global_load_dwordx4 v[8:11], v[8:9], off offset:3072
	v_exp_f32_e32 v84, v67
	global_load_dwordx4 v[32:35], v[18:19], off
	s_nop 0
	global_load_dwordx4 v[16:19], v[16:17], off offset:3072
	v_add_u32_e32 v67, 0, v107
	ds_read_b128 v[88:91], v67
	ds_read_b128 v[92:95], v67 offset:4096
	ds_read_b32 v151, v105
	ds_read_b128 v[152:155], v67 offset:8192
	ds_read_b128 v[156:159], v67 offset:12288
	ds_read_b32 v171, v104
	s_waitcnt vmcnt(11) lgkmcnt(5)
	v_mfma_f32_16x16x32_bf16 v[88:91], v[88:91], v[28:31], 0
	s_waitcnt lgkmcnt(4)
	v_mfma_f32_16x16x32_bf16 v[92:95], v[92:95], v[28:31], 0
	s_waitcnt lgkmcnt(2)
	v_mfma_f32_16x16x32_bf16 v[152:155], v[152:155], v[28:31], 0
	s_waitcnt lgkmcnt(1)
	v_mfma_f32_16x16x32_bf16 v[156:159], v[156:159], v[28:31], 0
	ds_read_b128 v[160:163], v67 offset:16384
	ds_read_b128 v[164:167], v67 offset:20480
	ds_read_b128 v[172:175], v67 offset:24576
	ds_read_b128 v[178:181], v67 offset:28672
	s_waitcnt lgkmcnt(3)
	v_mfma_f32_16x16x32_bf16 v[160:163], v[160:163], v[28:31], 0
	s_waitcnt lgkmcnt(2)
	v_mfma_f32_16x16x32_bf16 v[164:167], v[164:167], v[28:31], 0
	s_waitcnt lgkmcnt(1)
	v_mfma_f32_16x16x32_bf16 v[172:175], v[172:175], v[28:31], 0
	s_waitcnt lgkmcnt(0)
	v_mfma_f32_16x16x32_bf16 v[178:181], v[178:181], v[28:31], 0
	v_add_u32_e32 v246, 0, v109
	ds_read_b128 v[218:221], v246
	ds_read_b128 v[222:225], v246 offset:4096
	ds_read_b128 v[226:229], v246 offset:8192
	ds_read_b128 v[230:233], v246 offset:12288
	ds_read_b128 v[234:237], v246 offset:16384
	v_add_u32_e32 v67, 0, v109
	ds_read_b128 v[238:241], v246 offset:20480
	s_waitcnt vmcnt(10) lgkmcnt(5)
	v_mfma_f32_16x16x32_bf16 v[88:91], v[218:221], v[24:27], v[88:91]
	ds_read_b128 v[218:221], v246 offset:24576
	s_waitcnt lgkmcnt(5)
	v_mfma_f32_16x16x32_bf16 v[92:95], v[222:225], v[24:27], v[92:95]
	ds_read_b128 v[222:225], v246 offset:28672
	s_waitcnt lgkmcnt(5)
	v_mfma_f32_16x16x32_bf16 v[152:155], v[226:229], v[24:27], v[152:155]
	v_add_u32_e32 v247, 0, v111
	ds_read_b128 v[226:229], v247
	s_waitcnt lgkmcnt(5)
	v_mfma_f32_16x16x32_bf16 v[156:159], v[230:233], v[24:27], v[156:159]
	ds_read_b128 v[230:233], v247 offset:4096
	s_waitcnt lgkmcnt(5)
	v_mfma_f32_16x16x32_bf16 v[160:163], v[234:237], v[24:27], v[160:163]
	ds_read_b128 v[234:237], v247 offset:8192
	s_waitcnt lgkmcnt(5)
	v_mfma_f32_16x16x32_bf16 v[164:167], v[238:241], v[24:27], v[164:167]
	ds_read_b128 v[238:241], v247 offset:12288
	s_waitcnt lgkmcnt(5)
	v_mfma_f32_16x16x32_bf16 v[172:175], v[218:221], v[24:27], v[172:175]
	ds_read_b128 v[218:221], v247 offset:16384
	s_waitcnt lgkmcnt(5)
	v_mfma_f32_16x16x32_bf16 v[178:181], v[222:225], v[24:27], v[178:181]
	v_add_u32_e32 v67, 0, v111
	ds_read_b128 v[222:225], v247 offset:20480
	s_waitcnt vmcnt(9) lgkmcnt(5)
	v_mfma_f32_16x16x32_bf16 v[88:91], v[226:229], v[20:23], v[88:91]
	ds_read_b128 v[226:229], v247 offset:24576
	s_waitcnt lgkmcnt(5)
	v_mfma_f32_16x16x32_bf16 v[92:95], v[230:233], v[20:23], v[92:95]
	ds_read_b128 v[230:233], v247 offset:28672
	s_waitcnt lgkmcnt(5)
	v_mfma_f32_16x16x32_bf16 v[152:155], v[234:237], v[20:23], v[152:155]
	v_add_u32_e32 v248, 0, v113
	ds_read_b128 v[234:237], v248
	s_waitcnt lgkmcnt(5)
	v_mfma_f32_16x16x32_bf16 v[156:159], v[238:241], v[20:23], v[156:159]
	ds_read_b128 v[238:241], v248 offset:4096
	s_waitcnt lgkmcnt(5)
	v_mfma_f32_16x16x32_bf16 v[160:163], v[218:221], v[20:23], v[160:163]
	ds_read_b128 v[218:221], v248 offset:8192
	s_waitcnt lgkmcnt(5)
	v_mfma_f32_16x16x32_bf16 v[164:167], v[222:225], v[20:23], v[164:167]
	ds_read_b128 v[222:225], v248 offset:12288
	s_waitcnt lgkmcnt(5)
	v_mfma_f32_16x16x32_bf16 v[172:175], v[226:229], v[20:23], v[172:175]
	ds_read_b128 v[226:229], v248 offset:16384
	s_waitcnt lgkmcnt(5)
	v_mfma_f32_16x16x32_bf16 v[178:181], v[230:233], v[20:23], v[178:181]
	v_add_u32_e32 v67, 0, v113
	ds_read_b128 v[230:233], v248 offset:20480
	s_waitcnt vmcnt(8) lgkmcnt(5)
	v_mfma_f32_16x16x32_bf16 v[88:91], v[234:237], v[12:15], v[88:91]
	ds_read_b128 v[234:237], v248 offset:24576
	s_waitcnt lgkmcnt(5)
	v_mfma_f32_16x16x32_bf16 v[92:95], v[238:241], v[12:15], v[92:95]
	ds_read_b128 v[238:241], v248 offset:28672
	s_waitcnt lgkmcnt(5)
	v_mfma_f32_16x16x32_bf16 v[152:155], v[218:221], v[12:15], v[152:155]
	s_nop 0
	s_waitcnt lgkmcnt(4)
	v_mfma_f32_16x16x32_bf16 v[156:159], v[222:225], v[12:15], v[156:159]
	s_nop 0
	s_waitcnt lgkmcnt(3)
	v_mfma_f32_16x16x32_bf16 v[160:163], v[226:229], v[12:15], v[160:163]
	s_nop 0
	s_waitcnt lgkmcnt(2)
	v_mfma_f32_16x16x32_bf16 v[164:167], v[230:233], v[12:15], v[164:167]
	s_nop 0
	s_waitcnt lgkmcnt(1)
	v_mfma_f32_16x16x32_bf16 v[172:175], v[234:237], v[12:15], v[172:175]
	s_nop 0
	s_waitcnt lgkmcnt(0)
	v_mfma_f32_16x16x32_bf16 v[178:181], v[238:241], v[12:15], v[178:181]
	v_mov_b32_e32 v67, s6
	ds_read_b32 v67, v67
	s_waitcnt lgkmcnt(0)
; __device__ __forceinline__ unsigned cvt_pk(float lo, float hi) { unsigned r; asm volatile("v_cvt_pk_bf16_f32 %0, %1, %2" : "=v"(r) : "v"(lo), "v"(hi)); return r; }
; __device__ __forceinline__ float bflo(unsigned w) { return __uint_as_float(w << 16); }
; __device__ __forceinline__ float bfhi(unsigned w) { return __uint_as_float(w & 0xffff0000u); }
; template <int SPLIT> __device__ __forceinline__ void scan_item(const Params& p, unsigned char* smem, const int item, const int vh) {
;     ...
;             float rs = 0.f; u32x2 pp[8];
;             const float rowf = __expf(fminf(sc[1] - Ml, 80.f));
; #pragma unroll
;             for (int nb = 0; nb < 8; ++nb) { float pv[4];
; #pragma unroll
;                 for (int jj = 0; jj < 4; ++jj) { const int s = nb * 16 + kq * 4 + jj; pv[jj] = (s <= l) ? acc[nb][jj] * rowf : 0.f; rs += pv[jj]; }
;                 pp[nb].x = cvt_pk(pv[0], pv[1]); pp[nb].y = cvt_pk(pv[2], pv[3]); }
;             __builtin_amdgcn_sched_barrier(0);
;             float nq = 0.f;
; #pragma unroll
;             for (int ks = 0; ks < 4; ++ks) { const f32x4 n0 = *(const f32x4*)(n_s + ks * 32 + kq * 8), n1 = *(const f32x4*)(n_s + ks * 32 + kq * 8 + 4);
;                 const u32x4 qw = *(const u32x4*)&qf[ks];
;                 nq += bflo(qw.x) * n0[0] + bfhi(qw.x) * n0[1] + bflo(qw.y) * n0[2] + bfhi(qw.y) * n0[3] + bflo(qw.z) * n1[0] + bfhi(qw.z) * n1[1] + bflo(qw.w) * n1[2] + bfhi(qw.w) * n1[3]; }
	v_sub_f32_e32 v67, v67, v171
	v_min_f32_e32 v67, 0x42a00000, v67
	v_mul_f32_e32 v67, 0x3fb8aa3b, v67
	v_exp_f32_e32 v87, v67
	s_nop 0
	v_mul_f32_e32 v67, v88, v87
	v_mul_f32_e32 v88, v89, v87
	v_cndmask_b32_e64 v67, v67, 0, s[10:11]
	v_mul_f32_e32 v89, v90, v87
	v_mul_f32_e32 v90, v91, v87
	v_cndmask_b32_e64 v91, 0, v88, s[12:13]
	v_add_f32_e32 v168, 0, v67
	v_cndmask_b32_e64 v89, v89, 0, s[14:15]
	v_cvt_pk_bf16_f32 v88, v67, v91
	v_add_f32_e32 v67, v91, v168
	v_cndmask_b32_e64 v90, v90, 0, s[16:17]
	v_add_f32_e32 v67, v89, v67
	v_add_f32_e32 v67, v90, v67
	v_cvt_pk_bf16_f32 v89, v89, v90
	v_mul_f32_e32 v90, v92, v87
	v_cndmask_b32_e64 v90, v90, 0, s[18:19]
	v_mul_f32_e32 v91, v93, v87
	v_add_f32_e32 v67, v90, v67
	v_cndmask_b32_e64 v91, v91, 0, s[20:21]
	v_mul_f32_e32 v92, v94, v87
	v_add_f32_e32 v67, v91, v67
	v_cndmask_b32_e64 v92, v92, 0, s[22:23]
	v_mul_f32_e32 v93, v95, v87
	v_add_f32_e32 v67, v92, v67
	v_cndmask_b32_e64 v93, v93, 0, s[24:25]
	v_cvt_pk_bf16_f32 v90, v90, v91
	v_cvt_pk_bf16_f32 v91, v92, v93
	v_mul_f32_e32 v92, v152, v87
	v_add_f32_e32 v67, v93, v67
	v_cndmask_b32_e64 v92, v92, 0, s[26:27]
	v_mul_f32_e32 v93, v153, v87
	v_add_f32_e32 v67, v92, v67
	v_cndmask_b32_e64 v93, v93, 0, s[28:29]
	v_mul_f32_e32 v94, v154, v87
	v_add_f32_e32 v67, v93, v67
	v_cndmask_b32_e64 v94, v94, 0, s[30:31]
	v_mul_f32_e32 v95, v155, v87
	v_add_f32_e32 v67, v94, v67
	v_cndmask_b32_e64 v95, v95, 0, s[34:35]
	v_cvt_pk_bf16_f32 v92, v92, v93
	v_cvt_pk_bf16_f32 v93, v94, v95
	v_mul_f32_e32 v94, v156, v87
	v_add_f32_e32 v67, v95, v67
	v_cndmask_b32_e64 v94, v94, 0, s[36:37]
	v_mul_f32_e32 v95, v157, v87
	v_add_f32_e32 v67, v94, v67
	v_cndmask_b32_e64 v95, v95, 0, s[38:39]
	v_mul_f32_e32 v152, v158, v87
	v_add_f32_e32 v67, v95, v67
	v_cndmask_b32_e64 v152, v152, 0, s[40:41]
	v_mul_f32_e32 v153, v159, v87
	v_add_f32_e32 v67, v152, v67
	v_cndmask_b32_e64 v153, v153, 0, s[42:43]
	v_cvt_pk_bf16_f32 v94, v94, v95
	v_cvt_pk_bf16_f32 v95, v152, v153
	v_mul_f32_e32 v152, v160, v87
	v_add_f32_e32 v67, v153, v67
	v_cndmask_b32_e64 v152, v152, 0, s[44:45]
	v_mul_f32_e32 v153, v161, v87
	v_add_f32_e32 v67, v152, v67
	v_cndmask_b32_e64 v153, v153, 0, s[46:47]
	v_mul_f32_e32 v154, v162, v87
	v_add_f32_e32 v67, v153, v67
	v_cndmask_b32_e64 v154, v154, 0, s[48:49]
	v_mul_f32_e32 v155, v163, v87
	v_add_f32_e32 v67, v154, v67
	v_cndmask_b32_e64 v155, v155, 0, s[50:51]
	v_cvt_pk_bf16_f32 v168, v152, v153
	v_mul_f32_e32 v152, v164, v87
	v_add_f32_e32 v67, v155, v67
	v_cndmask_b32_e64 v152, v152, 0, s[52:53]
	v_add_f32_e32 v161, v152, v67
	v_mul_f32_e32 v67, v165, v87
	v_cndmask_b32_e64 v163, v67, 0, s[54:55]
	v_mul_f32_e32 v67, v166, v87
	v_cndmask_b32_e64 v183, v67, 0, s[56:57]
	v_mul_f32_e32 v67, v167, v87
	v_cndmask_b32_e64 v185, v67, 0, s[58:59]
	v_mul_f32_e32 v67, v172, v87
	v_cndmask_b32_e64 v189, v67, 0, s[60:61]
	v_mul_f32_e32 v67, v173, v87
	v_cndmask_b32_e64 v173, v67, 0, s[62:63]
	v_mul_f32_e32 v67, v174, v87
	v_cndmask_b32_e64 v191, v67, 0, s[64:65]
	v_mul_f32_e32 v67, v175, v87
	v_cvt_pk_bf16_f32 v169, v154, v155
	v_cvt_pk_bf16_f32 v186, v152, v163
	v_cndmask_b32_e64 v175, v67, 0, s[66:67]
	v_mul_f32_e32 v67, v178, v87
	v_mul_f32_e32 v152, v179, v87
	v_cndmask_b32_e64 v67, v67, 0, s[68:69]
	v_cndmask_b32_e64 v177, v152, 0, s[70:71]
	v_mul_f32_e32 v152, v180, v87
	v_mul_f32_e32 v87, v181, v87
	v_cvt_pk_bf16_f32 v187, v183, v185
	v_cvt_pk_bf16_f32 v192, v189, v173
	v_cvt_pk_bf16_f32 v193, v191, v175
	v_cndmask_b32_e64 v200, v152, 0, s[72:73]
	v_cndmask_b32_e64 v201, v87, 0, s[74:75]
	v_cvt_pk_bf16_f32 v178, v67, v177
	v_cvt_pk_bf16_f32 v179, v200, v201
	ds_read_b128 v[152:155], v137
	ds_read_b128 v[156:159], v137 offset:16
	v_lshlrev_b32_e32 v87, 16, v28
	v_and_b32_e32 v160, 0xffff0000, v28
	v_and_b32_e32 v195, 0xffff0000, v27
	s_waitcnt lgkmcnt(1)
	v_mul_f32_e32 v162, v152, v87
	v_lshlrev_b32_e32 v87, 16, v29
	v_mul_f32_e32 v182, v154, v87
	v_and_b32_e32 v87, 0xffff0000, v29
	v_mul_f32_e32 v160, v153, v160
	v_mul_f32_e32 v184, v155, v87
	v_lshlrev_b32_e32 v87, 16, v30
	ds_read_b128 v[152:155], v137 offset:128
	s_waitcnt lgkmcnt(1)
	v_mul_f32_e32 v188, v156, v87
	v_and_b32_e32 v87, 0xffff0000, v30
	v_mul_f32_e32 v172, v157, v87
	v_lshlrev_b32_e32 v87, 16, v31
	v_mul_f32_e32 v190, v158, v87
	v_and_b32_e32 v87, 0xffff0000, v31
	v_pk_add_f32 v[180:181], v[162:163], v[160:161]
	v_mul_f32_e32 v174, v159, v87
	ds_read_b128 v[156:159], v137 offset:144
	v_and_b32_e32 v161, 0xffff0000, v24
	v_lshlrev_b32_e32 v160, 16, v24
	s_waitcnt lgkmcnt(1)
	v_mul_f32_e32 v162, v153, v161
	v_pk_fma_f32 v[152:153], v[152:153], v[160:161], v[162:163] op_sel_hi:[1,1,0]
	v_and_b32_e32 v161, 0xffff0000, v25
	v_lshlrev_b32_e32 v160, 16, v25
	v_pk_fma_f32 v[152:153], v[154:155], v[160:161], v[152:153]
	v_mul_f32_e32 v154, v155, v161
	v_pk_add_f32 v[152:153], v[154:155], v[152:153] op_sel_hi:[0,1]
	v_and_b32_e32 v155, 0xffff0000, v26
	v_lshlrev_b32_e32 v154, 16, v26
	s_waitcnt lgkmcnt(0)
	v_pk_fma_f32 v[152:153], v[156:157], v[154:155], v[152:153]
	v_mul_f32_e32 v154, v157, v155
	v_pk_add_f32 v[156:157], v[154:155], v[152:153] op_sel_hi:[0,1]
	ds_read_b128 v[152:155], v137 offset:256
	ds_read_b128 v[160:163], v137 offset:272
	v_lshlrev_b32_e32 v194, 16, v27
	v_and_b32_e32 v165, 0xffff0000, v20
	v_pk_fma_f32 v[156:157], v[158:159], v[194:195], v[156:157]
	v_lshlrev_b32_e32 v164, 16, v20
	s_waitcnt lgkmcnt(1)
	v_mul_f32_e32 v158, v153, v165
	v_pk_fma_f32 v[152:153], v[152:153], v[164:165], v[158:159] op_sel_hi:[1,1,0]
	v_and_b32_e32 v165, 0xffff0000, v21
	v_lshlrev_b32_e32 v164, 16, v21
	v_pk_fma_f32 v[152:153], v[154:155], v[164:165], v[152:153]
	v_mul_f32_e32 v154, v155, v165
	v_pk_add_f32 v[152:153], v[154:155], v[152:153] op_sel_hi:[0,1]
	v_and_b32_e32 v155, 0xffff0000, v22
	v_lshlrev_b32_e32 v154, 16, v22
	s_waitcnt lgkmcnt(0)
; __device__ __forceinline__ float bflo(unsigned w) { return __uint_as_float(w << 16); }
; __device__ __forceinline__ float bfhi(unsigned w) { return __uint_as_float(w & 0xffff0000u); }
; template <int SPLIT> __device__ __forceinline__ void scan_item(const Params& p, unsigned char* smem, const int item, const int vh) {
;     ...
;             for (int ks = 0; ks < 4; ++ks) { const f32x4 n0 = *(const f32x4*)(n_s + ks * 32 + kq * 8), n1 = *(const f32x4*)(n_s + ks * 32 + kq * 8 + 4);
;                 const u32x4 qw = *(const u32x4*)&qf[ks];
;                 nq += bflo(qw.x) * n0[0] + bfhi(qw.x) * n0[1] + bflo(qw.y) * n0[2] + bfhi(qw.y) * n0[3] + bflo(qw.z) * n1[0] + bfhi(qw.z) * n1[1] + bflo(qw.w) * n1[2] + bfhi(qw.w) * n1[3]; }
;             rs += __shfl_xor(rs, 16); rs += __shfl_xor(rs, 32); nq += __shfl_xor(nq, 16); nq += __shfl_xor(nq, 32);
;             const float exl = __expf(m_old - Ml);
;             const float den = rs + exl * nq;
;             const float hinv = __builtin_amdgcn_rcpf(fmaxf(fabsf(den), __expf(-(gl + Ml))));
;             __syncthreads();
; #pragma unroll
;             for (int nb = 0; nb < 8; ++nb) *(u32x2*)(KP + swz(l, nb * 2 + (kq >> 1)) + (kq & 1) * 8) = pp[nb];
;             f32x4 acc2[NBV];
; #pragma unroll
;             for (int nb = 0; nb < NBV; ++nb) acc2[nb] = (f32x4){0.f, 0.f, 0.f, 0.f};
;             __builtin_amdgcn_sched_barrier(0);
;             mm16<NBV>(acc2, CS + vh * 16384, qf, lane);
	v_pk_fma_f32 v[152:153], v[160:161], v[154:155], v[152:153]
	v_mul_f32_e32 v154, v161, v155
	v_pk_add_f32 v[160:161], v[154:155], v[152:153] op_sel_hi:[0,1]
	ds_read_b128 v[152:155], v137 offset:384
	ds_read_b128 v[164:167], v137 offset:400
	v_and_b32_e32 v199, 0xffff0000, v12
	v_lshlrev_b32_e32 v198, 16, v12
	v_and_b32_e32 v197, 0xffff0000, v23
	s_waitcnt lgkmcnt(1)
	v_mul_f32_e32 v158, v153, v199
	v_pk_fma_f32 v[152:153], v[152:153], v[198:199], v[158:159] op_sel_hi:[1,1,0]
	v_and_b32_e32 v199, 0xffff0000, v13
	v_lshlrev_b32_e32 v198, 16, v13
	v_pk_fma_f32 v[152:153], v[154:155], v[198:199], v[152:153]
	v_mul_f32_e32 v154, v155, v199
	v_pk_add_f32 v[152:153], v[154:155], v[152:153] op_sel_hi:[0,1]
	v_and_b32_e32 v155, 0xffff0000, v14
	v_lshlrev_b32_e32 v154, 16, v14
	s_waitcnt lgkmcnt(0)
	v_pk_fma_f32 v[152:153], v[164:165], v[154:155], v[152:153]
	v_mul_f32_e32 v154, v165, v155
	v_pk_add_f32 v[164:165], v[182:183], v[180:181]
	v_pk_add_f32 v[152:153], v[154:155], v[152:153] op_sel_hi:[0,1]
	v_pk_add_f32 v[164:165], v[184:185], v[164:165]
	v_and_b32_e32 v155, 0xffff0000, v15
	v_lshlrev_b32_e32 v154, 16, v15
	v_pk_add_f32 v[164:165], v[188:189], v[164:165]
	v_lshlrev_b32_e32 v196, 16, v23
	v_pk_fma_f32 v[152:153], v[166:167], v[154:155], v[152:153]
	v_and_b32_e32 v154, 64, v150
	v_pk_add_f32 v[164:165], v[172:173], v[164:165]
	v_pk_fma_f32 v[160:161], v[162:163], v[196:197], v[160:161]
	v_add_u32_e32 v162, 64, v154
	v_pk_add_f32 v[164:165], v[190:191], v[164:165]
	v_mul_f32_e32 v154, v159, v195
	v_pk_add_f32 v[164:165], v[174:175], v[164:165]
	v_pk_add_f32 v[156:157], v[154:155], v[156:157] op_sel_hi:[0,1]
	v_mul_f32_e32 v154, v163, v197
	v_xor_b32_e32 v87, 16, v150
	v_pk_add_f32 v[164:165], v[66:67], v[164:165]
	v_mov_b32_e32 v157, v177
	v_pk_add_f32 v[158:159], v[154:155], v[160:161] op_sel_hi:[0,1]
	v_mul_f32_e32 v154, v167, v155
	v_cmp_lt_i32_e32 vcc, v87, v162
	v_pk_add_f32 v[156:157], v[156:157], v[164:165]
	v_mov_b32_e32 v159, v200
	v_pk_add_f32 v[152:153], v[154:155], v[152:153] op_sel_hi:[0,1]
	v_cndmask_b32_e32 v87, v150, v87, vcc
	v_pk_add_f32 v[156:157], v[158:159], v[156:157]
	v_mov_b32_e32 v153, v201
	v_lshlrev_b32_e32 v87, 2, v87
	v_pk_add_f32 v[152:153], v[152:153], v[156:157]
	ds_bpermute_b32 v155, v87, v153
	ds_bpermute_b32 v154, v87, v152
	v_xor_b32_e32 v67, 32, v150
	v_cmp_lt_i32_e32 vcc, v67, v162
	v_sub_f32_e32 v86, v86, v171
	v_mul_f32_e32 v86, 0x3fb8aa3b, v86
	v_cndmask_b32_e32 v67, v150, v67, vcc
	v_lshlrev_b32_e32 v67, 2, v67
	s_waitcnt lgkmcnt(0)
	v_pk_add_f32 v[152:153], v[152:153], v[154:155]
	v_mov_b32_e32 v154, v152
	v_mov_b32_e32 v155, v153
	s_nop 1
	v_permlane32_swap_b32_e32 v154, v152
	v_permlane32_swap_b32_e32 v155, v153
	v_add_f32_e32 v151, v171, v151
	v_exp_f32_e32 v86, v86
	v_mul_f32_e32 v151, 0xbfb8aa3b, v151
	v_exp_f32_e32 v151, v151
	s_waitcnt lgkmcnt(0)
	v_pk_add_f32 v[152:153], v[152:153], v[154:155]
	s_nop 0
	v_fmac_f32_e32 v153, v86, v152
	v_max_f32_e64 v151, |v153|, v151
	s_barrier
	ds_write_b64 v138, v[88:89]
	ds_write_b64 v139, v[90:91]
	ds_write_b64 v140, v[92:93]
	ds_write_b64 v141, v[94:95]
	ds_write_b64 v142, v[168:169]
	ds_write_b64 v143, v[186:187]
	ds_write_b64 v144, v[192:193]
	ds_write_b64 v145, v[178:179]
	v_add_u32_e32 v156, s89, v107
	ds_read_b128 v[88:91], v156
	ds_read_b128 v[92:95], v156 offset:4096
	ds_read_b128 v[152:155], v156 offset:8192
	ds_read_b128 v[156:159], v156 offset:12288
	s_waitcnt lgkmcnt(3)
	v_mfma_f32_16x16x32_bf16 v[88:91], v[88:91], v[28:31], 0
	s_waitcnt lgkmcnt(2)
	v_mfma_f32_16x16x32_bf16 v[92:95], v[92:95], v[28:31], 0
	s_waitcnt lgkmcnt(1)
	v_mfma_f32_16x16x32_bf16 v[152:155], v[152:155], v[28:31], 0
	s_waitcnt lgkmcnt(0)
	v_mfma_f32_16x16x32_bf16 v[28:31], v[156:159], v[28:31], 0
	v_add_u32_e32 v249, s89, v109
	ds_read_b128 v[218:221], v249
	ds_read_b128 v[222:225], v249 offset:4096
	ds_read_b128 v[226:229], v249 offset:8192
	ds_read_b128 v[230:233], v249 offset:12288
	v_add_u32_e32 v160, s89, v109
	s_nop 0
	s_waitcnt lgkmcnt(3)
	v_mfma_f32_16x16x32_bf16 v[88:91], v[218:221], v[24:27], v[88:91]
	s_nop 0
	s_waitcnt lgkmcnt(2)
	v_mfma_f32_16x16x32_bf16 v[92:95], v[222:225], v[24:27], v[92:95]
	s_nop 0
	s_waitcnt lgkmcnt(1)
	v_mfma_f32_16x16x32_bf16 v[152:155], v[226:229], v[24:27], v[152:155]
	s_nop 0
	s_waitcnt lgkmcnt(0)
	v_mfma_f32_16x16x32_bf16 v[24:27], v[230:233], v[24:27], v[28:31]
	v_add_u32_e32 v156, s89, v111
	s_nop 1
	ds_read_b128 v[28:31], v156
	s_waitcnt lgkmcnt(0)
	v_mfma_f32_16x16x32_bf16 v[28:31], v[28:31], v[20:23], v[88:91]
	s_nop 2
	ds_read_b128 v[88:91], v156 offset:4096
	s_waitcnt lgkmcnt(0)
	v_mfma_f32_16x16x32_bf16 v[88:91], v[88:91], v[20:23], v[92:95]
	s_nop 2
	ds_read_b128 v[92:95], v156 offset:8192
	s_waitcnt lgkmcnt(0)
	v_mfma_f32_16x16x32_bf16 v[92:95], v[92:95], v[20:23], v[152:155]
	s_nop 2
	ds_read_b128 v[152:155], v156 offset:12288
	s_waitcnt lgkmcnt(0)
	v_mfma_f32_16x16x32_bf16 v[20:23], v[152:155], v[20:23], v[24:27]
	v_add_u32_e32 v156, s89, v113
	s_nop 1
	ds_read_b128 v[226:229], v156
	ds_read_b128 v[230:233], v156 offset:4096
	ds_read_b128 v[234:237], v156 offset:8192
	ds_read_b128 v[24:27], v156 offset:12288
	s_waitcnt lgkmcnt(3)
	v_mfma_f32_16x16x32_bf16 v[152:155], v[226:229], v[12:15], v[28:31]
	s_nop 0
	s_waitcnt lgkmcnt(2)
	v_mfma_f32_16x16x32_bf16 v[88:91], v[230:233], v[12:15], v[88:91]
	s_nop 0
	s_waitcnt lgkmcnt(1)
	v_mfma_f32_16x16x32_bf16 v[92:95], v[234:237], v[12:15], v[92:95]
	s_nop 0
	s_waitcnt lgkmcnt(0)
; __device__ __forceinline__ unsigned cvt_pk(float lo, float hi) { unsigned r; asm volatile("v_cvt_pk_bf16_f32 %0, %1, %2" : "=v"(r) : "v"(lo), "v"(hi)); return r; }
; #define Q_LOAD(j) do { const size_t r = (size_t)(rfirst + rstep * ((j) * 128 + wid * 16 + li)); \
;           _Pragma("unroll") for (int ks = 0; ks < 4; ++ks) qf[ks] = *(const bf16x8*)(Q0 + r * 512 + h * 128 + ks * 32 + kq * 8); } while (0)
; template <int SPLIT> __device__ __forceinline__ void scan_item(const Params& p, unsigned char* smem, const int item, const int vh) {
;     ...
;             mm16<NBV>(acc2, CS + vh * 16384, qf, lane);
;             __builtin_amdgcn_sched_barrier(0);
;             Q_LOAD(jn);
; #pragma unroll
;             for (int nb = 0; nb < NBV; ++nb) acc2[nb] *= exl;
;             __builtin_amdgcn_sched_barrier(0);
;             { bf16x8 pf[4]; ldfrag(pf, KP, wid, lane); mm16<NBV>(acc2, VT + vh * 16384, pf, lane); }
;             __builtin_amdgcn_sched_barrier(0);
;             { bf16_t* hp = P0 + rowl * LDP + dir * 512 + h * 128 + vh * 64 + kq * 4;
; #pragma unroll
;               for (int nb = 0; nb < NBV; ++nb) { u32x2 o; o.x = cvt_pk(acc2[nb][0] * hinv, acc2[nb][1] * hinv); o.y = cvt_pk(acc2[nb][2] * hinv, acc2[nb][3] * hinv);
;                   *(u32x2*)(hp + nb * 16) = o; } }
;             __builtin_amdgcn_sched_barrier(0);
;             float nnew;
;             { bf16x8 vf[4]; ldfrag(vf, VT, vblk, lane);
; #pragma unroll
;               for (int nb = 0; nb < NBV; ++nb) Cacc[nb] *= decay;
;               mm16<NBV>(Cacc, KT + kh * 16384, vf, lane);
	v_mfma_f32_16x16x32_bf16 v[156:159], v[24:27], v[12:15], v[20:23]
	s_nop 0
	v_add_u32_e32 v12, s0, v96
	v_mul_lo_u32 v12, v12, s3
	v_add_u32_e32 v12, s33, v12
	v_ashrrev_i32_e32 v13, 31, v12
	v_lshlrev_b64 v[12:13], 10, v[12:13]
	v_lshl_add_u64 v[12:13], v[76:77], 0, v[12:13]
	global_load_dwordx4 v[28:31], v[12:13], off
	global_load_dwordx4 v[24:27], v[12:13], off offset:64
	global_load_dwordx4 v[20:23], v[12:13], off offset:128
	s_nop 0
	global_load_dwordx4 v[12:15], v[12:13], off offset:192
	v_pk_mul_f32 v[154:155], v[86:87], v[154:155] op_sel_hi:[0,1]
	v_pk_mul_f32 v[152:153], v[86:87], v[152:153] op_sel_hi:[0,1]
	v_pk_mul_f32 v[90:91], v[86:87], v[90:91] op_sel_hi:[0,1]
	v_pk_mul_f32 v[88:89], v[86:87], v[88:89] op_sel_hi:[0,1]
	v_pk_mul_f32 v[94:95], v[86:87], v[94:95] op_sel_hi:[0,1]
	v_rcp_f32_e32 v151, v151
	v_pk_mul_f32 v[92:93], v[86:87], v[92:93] op_sel_hi:[0,1]
	v_pk_mul_f32 v[158:159], v[86:87], v[158:159] op_sel_hi:[0,1]
	v_pk_mul_f32 v[156:157], v[86:87], v[156:157] op_sel_hi:[0,1]
	v_add_u32_e32 v86, s90, v107
	ds_read_b128 v[160:163], v86 offset:32768
	v_add_u32_e32 v164, v115, v114
	ds_read_b128 v[164:167], v164
	ds_read_b128 v[172:175], v86 offset:36864
	v_add_u32_e32 v168, v116, v114
	ds_read_b128 v[178:181], v168
	s_waitcnt lgkmcnt(1)
	v_mfma_f32_16x16x32_bf16 v[88:91], v[172:175], v[164:167], v[88:91]
	v_add_u32_e32 v168, v118, v114
	ds_read_b128 v[172:175], v86 offset:45056
	v_mfma_f32_16x16x32_bf16 v[152:155], v[160:163], v[164:167], v[152:155]
	ds_read_b128 v[160:163], v86 offset:40960
	v_add_u32_e32 v86, v117, v114
	s_waitcnt lgkmcnt(0)
	v_mfma_f32_16x16x32_bf16 v[92:95], v[160:163], v[164:167], v[92:95]
	ds_read_b128 v[160:163], v86
	ds_read_b128 v[182:185], v168
	v_mfma_f32_16x16x32_bf16 v[156:159], v[172:175], v[164:167], v[156:159]
	v_add_u32_e32 v86, s90, v109
	ds_read_b128 v[226:229], v86 offset:32768
	ds_read_b128 v[230:233], v86 offset:36864
	ds_read_b128 v[234:237], v86 offset:40960
	ds_read_b128 v[164:167], v86 offset:45056
	s_waitcnt lgkmcnt(3)
	v_mfma_f32_16x16x32_bf16 v[152:155], v[226:229], v[178:181], v[152:155]
	s_nop 0
	s_waitcnt lgkmcnt(2)
	v_mfma_f32_16x16x32_bf16 v[88:91], v[230:233], v[178:181], v[88:91]
	s_nop 0
	s_waitcnt lgkmcnt(1)
	v_mfma_f32_16x16x32_bf16 v[92:95], v[234:237], v[178:181], v[92:95]
	s_nop 0
	s_waitcnt lgkmcnt(0)
	v_mfma_f32_16x16x32_bf16 v[156:159], v[164:167], v[178:181], v[156:159]
	s_nop 0
	v_add_u32_e32 v86, s90, v111
	ds_read_b128 v[226:229], v86 offset:32768
	ds_read_b128 v[230:233], v86 offset:36864
	ds_read_b128 v[234:237], v86 offset:40960
	ds_read_b128 v[164:167], v86 offset:45056
	s_waitcnt lgkmcnt(3)
	v_mfma_f32_16x16x32_bf16 v[152:155], v[226:229], v[160:163], v[152:155]
	s_nop 0
	s_waitcnt lgkmcnt(2)
	v_mfma_f32_16x16x32_bf16 v[88:91], v[230:233], v[160:163], v[88:91]
	s_nop 0
	s_waitcnt lgkmcnt(1)
	v_mfma_f32_16x16x32_bf16 v[92:95], v[234:237], v[160:163], v[92:95]
	s_nop 0
	s_waitcnt lgkmcnt(0)
	v_mfma_f32_16x16x32_bf16 v[156:159], v[164:167], v[160:163], v[156:159]
	s_nop 0
	v_add_u32_e32 v250, s90, v113
	ds_read_b128 v[218:221], v250 offset:32768
	ds_read_b128 v[222:225], v250 offset:36864
	ds_read_b128 v[226:229], v250 offset:40960
	ds_read_b128 v[230:233], v250 offset:45056
	v_add_u32_e32 v86, s90, v113
	s_nop 0
	s_waitcnt lgkmcnt(3)
	v_mfma_f32_16x16x32_bf16 v[152:155], v[218:221], v[182:185], v[152:155]
	s_nop 0
	s_waitcnt lgkmcnt(2)
	v_mfma_f32_16x16x32_bf16 v[88:91], v[222:225], v[182:185], v[88:91]
	s_nop 0
	s_waitcnt lgkmcnt(1)
	v_mfma_f32_16x16x32_bf16 v[92:95], v[226:229], v[182:185], v[92:95]
	s_nop 0
	s_waitcnt lgkmcnt(0)
	v_mfma_f32_16x16x32_bf16 v[156:159], v[230:233], v[182:185], v[156:159]
	v_mul_f32_e32 v86, v151, v152
	v_mul_f32_e32 v152, v151, v153
	v_cvt_pk_bf16_f32 v152, v86, v152
	v_mul_f32_e32 v86, v151, v154
	v_mul_f32_e32 v153, v151, v155
	v_mad_i64_i32 v[160:161], s[4:5], v131, s88, v[78:79]
	v_cvt_pk_bf16_f32 v153, v86, v153
	v_mul_f32_e32 v86, v151, v88
	v_mul_f32_e32 v88, v151, v89
	global_store_dwordx2 v[160:161], v[152:153], off
	v_cvt_pk_bf16_f32 v88, v86, v88
	v_mul_f32_e32 v86, v151, v90
	v_mul_f32_e32 v89, v151, v91
	v_cvt_pk_bf16_f32 v89, v86, v89
	global_store_dwordx2 v[160:161], v[88:89], off offset:32
	v_mul_f32_e32 v86, v151, v92
	v_mul_f32_e32 v88, v151, v93
	v_cvt_pk_bf16_f32 v88, v86, v88
	v_mul_f32_e32 v86, v151, v94
	v_mul_f32_e32 v89, v151, v95
	v_cvt_pk_bf16_f32 v89, v86, v89
	global_store_dwordx2 v[160:161], v[88:89], off offset:64
	v_mul_f32_e32 v86, v151, v156
	v_mul_f32_e32 v88, v151, v157
	v_cvt_pk_bf16_f32 v88, v86, v88
	v_mul_f32_e32 v86, v151, v158
	v_mul_f32_e32 v89, v151, v159
	v_cvt_pk_bf16_f32 v89, v86, v89
	global_store_dwordx2 v[160:161], v[88:89], off offset:96
	v_add_u32_e32 v86, v120, v107
	ds_read_b128 v[88:91], v86
	v_add_u32_e32 v92, v115, v119
	ds_read_b128 v[92:95], v92 offset:32768
	ds_read_b128 v[152:155], v86 offset:4096
	v_add_u32_e32 v151, v116, v119
	v_pk_mul_f32 v[50:51], v[50:51], v[84:85] op_sel_hi:[1,0]
	v_pk_mul_f32 v[48:49], v[48:49], v[84:85] op_sel_hi:[1,0]
	ds_read_b128 v[156:159], v151 offset:32768
	ds_read_b128 v[160:163], v86 offset:8192
	v_add_u32_e32 v151, v117, v119
	v_pk_mul_f32 v[54:55], v[54:55], v[84:85] op_sel_hi:[1,0]
	s_waitcnt lgkmcnt(3)
	v_mfma_f32_16x16x32_bf16 v[48:51], v[88:91], v[92:95], v[48:51]
	ds_read_b128 v[88:91], v86 offset:12288
	v_pk_mul_f32 v[52:53], v[52:53], v[84:85] op_sel_hi:[1,0]
	v_pk_mul_f32 v[58:59], v[58:59], v[84:85] op_sel_hi:[1,0]
	v_pk_mul_f32 v[56:57], v[56:57], v[84:85] op_sel_hi:[1,0]
	s_waitcnt lgkmcnt(3)
; __device__ __forceinline__ unsigned cvt_pk(float lo, float hi) { unsigned r; asm volatile("v_cvt_pk_bf16_f32 %0, %1, %2" : "=v"(r) : "v"(lo), "v"(hi)); return r; }
; __device__ __forceinline__ float bflo(unsigned w) { return __uint_as_float(w << 16); }
; __device__ __forceinline__ float bfhi(unsigned w) { return __uint_as_float(w & 0xffff0000u); }
; template <int SPLIT> __device__ __forceinline__ void scan_item(const Params& p, unsigned char* smem, const int item, const int vh) {
;     ...
;               mm16<NBV>(Cacc, KT + kh * 16384, vf, lane);
;               float part = 0.f;
; #pragma unroll
;               for (int ks = 0; ks < 4; ++ks) { const u32x4 kw = *(const u32x4*)(KT + swz(wid * 16 + li, ks * 4 + kq));
;                   part += bflo(kw.x) + bfhi(kw.x) + bflo(kw.y) + bfhi(kw.y) + bflo(kw.z) + bfhi(kw.z) + bflo(kw.w) + bfhi(kw.w); }
;               part += __shfl_xor(part, 16); part += __shfl_xor(part, 32);
;               nnew = decay * n_s[wid * 16 + li] + part; }
;             __syncthreads();
; #pragma unroll
;             for (int nb = 0; nb < NBV; ++nb) { u32x2 o; o.x = cvt_pk(Cacc[nb][0], Cacc[nb][1]); o.y = cvt_pk(Cacc[nb][2], Cacc[nb][3]);
;                 *(u32x2*)(CS + swz(vblk * 16 + li, (kh * 4 + nb) * 2 + (kq >> 1)) + (kq & 1) * 8) = o; }
;             if (kq == 0) n_s[wid * 16 + li] = nnew;
	v_mfma_f32_16x16x32_bf16 v[52:55], v[152:155], v[92:95], v[52:55]
	v_add_u32_e32 v86, v118, v119
	v_pk_mul_f32 v[62:63], v[62:63], v[84:85] op_sel_hi:[1,0]
	v_pk_mul_f32 v[60:61], v[60:61], v[84:85] op_sel_hi:[1,0]
	s_waitcnt lgkmcnt(1)
	v_mfma_f32_16x16x32_bf16 v[56:59], v[160:163], v[92:95], v[56:59]
	ds_read_b128 v[152:155], v151 offset:32768
	ds_read_b128 v[160:163], v86 offset:32768
	s_waitcnt lgkmcnt(2)
	v_mfma_f32_16x16x32_bf16 v[60:63], v[88:91], v[92:95], v[60:63]
	v_add_u32_e32 v251, v120, v109
	ds_read_b128 v[218:221], v251
	ds_read_b128 v[222:225], v251 offset:4096
	ds_read_b128 v[226:229], v251 offset:8192
	ds_read_b128 v[230:233], v251 offset:12288
	v_add_u32_e32 v252, v120, v111
	ds_read_b128 v[234:237], v252
	v_add_u32_e32 v86, v120, v109
	ds_read_b128 v[238:241], v252 offset:4096
	s_waitcnt lgkmcnt(5)
	v_mfma_f32_16x16x32_bf16 v[48:51], v[218:221], v[156:159], v[48:51]
	ds_read_b128 v[218:221], v252 offset:8192
	s_waitcnt lgkmcnt(5)
	v_mfma_f32_16x16x32_bf16 v[52:55], v[222:225], v[156:159], v[52:55]
	ds_read_b128 v[222:225], v252 offset:12288
	s_waitcnt lgkmcnt(5)
	v_mfma_f32_16x16x32_bf16 v[56:59], v[226:229], v[156:159], v[56:59]
	v_add_u32_e32 v253, v120, v113
	ds_read_b128 v[226:229], v253
	s_waitcnt lgkmcnt(5)
	v_mfma_f32_16x16x32_bf16 v[60:63], v[230:233], v[156:159], v[60:63]
	v_add_u32_e32 v86, v120, v111
	ds_read_b128 v[230:233], v253 offset:4096
	s_waitcnt lgkmcnt(5)
	v_mfma_f32_16x16x32_bf16 v[48:51], v[234:237], v[152:155], v[48:51]
	ds_read_b128 v[234:237], v253 offset:8192
	s_waitcnt lgkmcnt(5)
	v_mfma_f32_16x16x32_bf16 v[52:55], v[238:241], v[152:155], v[52:55]
	ds_read_b128 v[238:241], v253 offset:12288
	s_waitcnt lgkmcnt(5)
	v_mfma_f32_16x16x32_bf16 v[56:59], v[218:221], v[152:155], v[56:59]
	s_nop 0
	s_waitcnt lgkmcnt(4)
	v_mfma_f32_16x16x32_bf16 v[60:63], v[222:225], v[152:155], v[60:63]
	v_add_u32_e32 v86, v120, v113
	s_nop 0
	s_waitcnt lgkmcnt(3)
	v_mfma_f32_16x16x32_bf16 v[48:51], v[226:229], v[160:163], v[48:51]
	s_nop 0
	s_waitcnt lgkmcnt(2)
	v_mfma_f32_16x16x32_bf16 v[52:55], v[230:233], v[160:163], v[52:55]
	s_nop 0
	s_waitcnt lgkmcnt(1)
	v_mfma_f32_16x16x32_bf16 v[56:59], v[234:237], v[160:163], v[56:59]
	s_nop 0
	s_waitcnt lgkmcnt(0)
	v_mfma_f32_16x16x32_bf16 v[60:63], v[238:241], v[160:163], v[60:63]
	v_add_u32_e32 v86, v121, v106
	ds_read_b128 v[88:91], v86
	s_waitcnt lgkmcnt(0)
	v_lshlrev_b32_e32 v86, 16, v88
	v_and_b32_e32 v88, 0xffff0000, v88
	v_add_f32_e32 v86, v86, v88
	v_lshlrev_b32_e32 v88, 16, v89
	v_add_f32_e32 v86, v86, v88
	v_and_b32_e32 v88, 0xffff0000, v89
	v_add_f32_e32 v86, v86, v88
	v_lshlrev_b32_e32 v88, 16, v90
	v_add_f32_e32 v86, v86, v88
	v_and_b32_e32 v88, 0xffff0000, v90
	v_add_f32_e32 v86, v86, v88
	v_lshlrev_b32_e32 v88, 16, v91
	v_add_f32_e32 v86, v86, v88
	v_and_b32_e32 v88, 0xffff0000, v91
	v_add_f32_e32 v86, v86, v88
	v_add_u32_e32 v88, v121, v108
	ds_read_b128 v[88:91], v88
	v_add_f32_e32 v86, 0, v86
	s_waitcnt lgkmcnt(0)
	v_lshlrev_b32_e32 v92, 16, v88
	v_and_b32_e32 v88, 0xffff0000, v88
	v_add_f32_e32 v88, v92, v88
	v_lshlrev_b32_e32 v92, 16, v89
	v_add_f32_e32 v88, v88, v92
	v_and_b32_e32 v89, 0xffff0000, v89
	v_add_f32_e32 v88, v88, v89
	v_lshlrev_b32_e32 v89, 16, v90
	v_add_f32_e32 v88, v88, v89
	v_and_b32_e32 v89, 0xffff0000, v90
	v_add_f32_e32 v88, v88, v89
	v_lshlrev_b32_e32 v89, 16, v91
	v_add_f32_e32 v88, v88, v89
	v_and_b32_e32 v89, 0xffff0000, v91
	v_add_f32_e32 v88, v88, v89
	v_add_f32_e32 v86, v86, v88
	v_add_u32_e32 v88, v121, v110
	ds_read_b128 v[88:91], v88
	s_waitcnt lgkmcnt(0)
	v_lshlrev_b32_e32 v92, 16, v88
	v_and_b32_e32 v88, 0xffff0000, v88
	v_add_f32_e32 v88, v92, v88
	v_lshlrev_b32_e32 v92, 16, v89
	v_add_f32_e32 v88, v88, v92
	v_and_b32_e32 v89, 0xffff0000, v89
	v_add_f32_e32 v88, v88, v89
	v_lshlrev_b32_e32 v89, 16, v90
	v_add_f32_e32 v88, v88, v89
	v_and_b32_e32 v89, 0xffff0000, v90
	v_add_f32_e32 v88, v88, v89
	v_lshlrev_b32_e32 v89, 16, v91
	v_add_f32_e32 v88, v88, v89
	v_and_b32_e32 v89, 0xffff0000, v91
	v_add_f32_e32 v88, v88, v89
	v_add_f32_e32 v86, v86, v88
	v_add_u32_e32 v88, v121, v112
	ds_read_b128 v[88:91], v88
	s_waitcnt lgkmcnt(0)
	v_lshlrev_b32_e32 v92, 16, v88
	v_and_b32_e32 v88, 0xffff0000, v88
	v_add_f32_e32 v88, v92, v88
	v_lshlrev_b32_e32 v92, 16, v89
	v_add_f32_e32 v88, v88, v92
	v_and_b32_e32 v89, 0xffff0000, v89
	v_add_f32_e32 v88, v88, v89
	v_lshlrev_b32_e32 v89, 16, v90
	v_add_f32_e32 v88, v88, v89
	v_and_b32_e32 v89, 0xffff0000, v90
	v_add_f32_e32 v88, v88, v89
	v_lshlrev_b32_e32 v89, 16, v91
	v_add_f32_e32 v88, v88, v89
	v_and_b32_e32 v89, 0xffff0000, v91
	v_add_f32_e32 v88, v88, v89
	v_add_f32_e32 v86, v86, v88
	ds_bpermute_b32 v87, v87, v86
	s_waitcnt lgkmcnt(0)
	v_add_f32_e32 v86, v86, v87
	v_mov_b32_e32 v67, v86
	s_nop 1
	v_permlane32_swap_b32_e32 v67, v86
	ds_read_b32 v87, v122
	s_waitcnt lgkmcnt(0)
	s_barrier
	v_cvt_pk_bf16_f32 v88, v48, v49
	v_cvt_pk_bf16_f32 v89, v50, v51
	ds_write_b64 v146, v[88:89]
	v_cvt_pk_bf16_f32 v88, v52, v53
	v_cvt_pk_bf16_f32 v89, v54, v55
	ds_write_b64 v147, v[88:89]
	v_cvt_pk_bf16_f32 v88, v56, v57
	v_cvt_pk_bf16_f32 v89, v58, v59
	ds_write_b64 v148, v[88:89]
	v_cvt_pk_bf16_f32 v88, v60, v61
	v_cvt_pk_bf16_f32 v89, v62, v63
	ds_write_b64 v149, v[88:89]
	s_and_saveexec_b64 s[86:87], s[8:9]
	s_cbranch_execz .LBB0_311
	v_add_f32_e32 v67, v86, v67
	v_fmac_f32_e32 v67, v84, v87
	ds_write_b32 v122, v67
	s_branch .LBB0_311
